# scan loops: outputs paired with v_permlane32_swap and stored as dwordx4 (half the row transactions)
# speedup vs baseline: 1.0255x; 1.0222x over previous
; template <int DK>
; DI void scan_wg(const Params& p, char* smem, int grp, int dir, int hb) {
;   constexpr int NT = DK / 32, NF = DK / 16;
;   constexpr int QS = DK + 8;
;   constexpr int KTS = 40;
;   constexpr int OFF_K = 32 * QS * 2, OFF_KT = 2 * 32 * QS * 2, OFF_D = OFF_KT + DK * KTS * 2, BUFB = OFF_D + DK * 4;
;   constexpr int QN = DK / 64;
;   constexpr int CPR = DK / 8;
;   static_assert(2 * BUFB <= LDS_BYTES, "scan LDS");
;   const int tid = otid(), vs = tid >> 6, lane = tid & 63, r = lane & 31, h = lane >> 5;
;   const int b = hb >> 2, head = hb & 3;
;   const size_t chain = (size_t)dir * 16 + hb;
;   const u16* Qb = (const u16*)(p.S + (DK == 128 ? OFF_HQ : OFF_GQ)) + chain * LPOS * DK;
;   const u16* Kb = (const u16*)(p.S + (DK == 128 ? OFF_HK : OFF_GK)) + chain * LPOS * DK;
;   const u16* KTb = (const u16*)(p.S + (DK == 128 ? OFF_HKT : OFF_GKT)) + chain * NBLK * DK * 32;
;   const u16* VTb = (const u16*)(p.S + (DK == 128 ? OFF_HVT : OFF_GVT)) + (size_t)hb * NBLK * 128 * 32 + (vs * 32 + r) * 32 + h * 8;
;   const float* Db = (const float*)(p.S + (DK == 128 ? OFF_HD : OFF_GD)) + chain * NBLK * DK;
;   u16* Ob = p.U + (size_t)dir * NROW * D + grp * 512 + head * 128 + vs * 32;
;   f32x16 S[NT];
; #pragma unroll
;   for (int kt = 0; kt < NT; kt++)
; #pragma unroll
;     for (int e = 0; e < 16; e++) S[kt][e] = 0.f;
;   bf16x8 sq[QN], sk[QN], skt[QN], vn0, vn1;
;   float4 sd = make_float4(0.f, 0.f, 0.f, 0.f);
;   auto blk_of = [&](int step) { return dir ? (step < 8 ? 7 - step : 271 - step) : step; };
;   auto gload = [&](int step) {
;     const size_t pos0 = (size_t)blk_of(step) * 32;
; #pragma unroll
;     for (int i = 0; i < QN; i++) {
;       const int id = tid + i * 256;
;       sq[i] = *(const bf16x8*)(Qb + (pos0 + id / CPR) * DK + (id % CPR) * 8);
;       sk[i] = *(const bf16x8*)(Kb + (pos0 + id / CPR) * DK + (id % CPR) * 8);
;       skt[i] = *(const bf16x8*)(KTb + (size_t)blk_of(step) * DK * 32 + id * 8);
;     }
;     if (tid < DK / 4) sd = *(const float4*)(Db + (size_t)blk_of(step) * DK + tid * 4);
;     vn0 = *(const bf16x8*)(VTb + (size_t)blk_of(step) * 128 * 32);
;     vn1 = *(const bf16x8*)(VTb + (size_t)blk_of(step) * 128 * 32 + 16);
;   };
;   auto lstore = [&](int buf) {
;     char* base = smem + buf * BUFB;
; #pragma unroll
;     for (int i = 0; i < QN; i++) {
;       const int id = tid + i * 256;
.LBB0_565:
	s_or_b64 exec, exec, s[4:5]
	v_ashrrev_i32_e32 v10, 1, v8
	s_movk_i32 s21, 0xffe0
	v_readlane_b32 s4, v251, 42
	v_bfi_b32 v11, s21, v10, v8
	s_add_u32 s4, s4, s75
	v_readlane_b32 s5, v251, 43
	s_waitcnt vmcnt(3)
	v_lshlrev_b32_e32 v12, 5, v11
	v_bfe_u32 v9, v8, 5, 1
	s_addc_u32 s5, s5, 0
	v_ashrrev_i32_e32 v13, 31, v12
	v_lshl_add_u64 v[12:13], v[12:13], 1, s[4:5]
	v_lshlrev_b32_e32 v196, 4, v9
	v_lshl_add_u64 v[122:123], v[12:13], 0, v[196:197]
	s_lshl_b32 s24, s20, 13
	v_lshl_add_u64 v[12:13], v[122:123], 0, s[24:25]
	global_load_dwordx4 v[84:87], v[12:13], off
	global_load_dwordx4 v[80:83], v[12:13], off offset:32
	s_movk_i32 s4, 0x90
	v_mul_lo_u32 v6, v6, s4
	s_waitcnt vmcnt(15)
	v_lshl_add_u32 v134, v7, 4, v6
	v_lshrrev_b32_e32 v6, 2, v8
	v_mul_lo_u32 v6, v6, 40
	v_and_b32_e32 v7, 24, v2
	v_add_lshl_u32 v135, v6, v7, 1
	s_waitcnt vmcnt(14)
	v_lshlrev_b32_e32 v136, 4, v8
	s_waitcnt vmcnt(4)
	ds_write_b128 v134, v[64:67]
	s_waitcnt vmcnt(3)
	ds_write_b128 v134, v[68:71] offset:4608
	s_waitcnt vmcnt(2)
	ds_write_b128 v135, v[76:79] offset:9216
	s_and_saveexec_b64 s[4:5], s[40:41]
	ds_write_b128 v136, v[72:75] offset:14336
	s_or_b64 exec, exec, s[4:5]
	v_and_b32_e32 v137, 31, v8
	v_lshlrev_b32_e32 v138, 2, v9
	v_cmp_le_u32_e32 vcc, v138, v137
	v_lshl_add_u64 v[124:125], s[44:45], 0, v[0:1]
	v_lshl_add_u64 v[126:127], s[0:1], 0, v[0:1]
	v_cndmask_b32_e64 v0, 0, 1, vcc
	v_cmp_ge_u32_e32 vcc, v138, v137
	v_lshl_add_u64 v[128:129], v[2:3], 1, s[46:47]
	v_lshl_add_u64 v[132:133], v[4:5], 2, s[42:43]
	v_cndmask_b32_e64 v2, 0, 1, vcc
	v_cndmask_b32_e64 v0, v2, v0, s[38:39]
	v_and_b32_e32 v0, 1, v0
	v_cmp_eq_u32_e64 s[42:43], 1, v0
	v_or_b32_e32 v0, 1, v138
	v_cmp_lt_u32_e32 vcc, v138, v137
	s_add_u32 s4, s14, s33
	s_addc_u32 s5, s15, 0
	v_cndmask_b32_e64 v2, 0, 1, vcc
	v_cmp_ge_u32_e32 vcc, v0, v137
	s_lshl_b32 s21, s82, 8
	s_lshr_b32 s20, s82, 2
	v_cndmask_b32_e64 v0, 0, 1, vcc
	v_cndmask_b32_e64 v0, v0, v2, s[38:39]
	v_and_b32_e32 v0, 1, v0
	v_cmp_eq_u32_e64 s[44:45], 1, v0
	v_or_b32_e32 v0, 2, v138
	v_cmp_le_u32_e32 vcc, v0, v137
	s_and_b32 s21, s21, 0x300
	v_and_b32_e32 v6, 0xffffffe0, v10
	v_cndmask_b32_e64 v2, 0, 1, vcc
	v_cmp_ge_u32_e32 vcc, v0, v137
	s_add_u32 s4, s4, s21
	v_ashrrev_i32_e32 v7, 31, v6
	v_cndmask_b32_e64 v0, 0, 1, vcc
	v_cndmask_b32_e64 v0, v0, v2, s[38:39]
	v_and_b32_e32 v0, 1, v0
	v_cmp_eq_u32_e64 s[46:47], 1, v0
	v_or_b32_e32 v0, 3, v138
	v_cmp_le_u32_e32 vcc, v0, v137
	s_addc_u32 s5, s5, 0
	v_lshlrev_b32_e32 v196, 3, v9
	v_cndmask_b32_e64 v2, 0, 1, vcc
	v_cmp_ge_u32_e32 vcc, v0, v137
	v_lshl_add_u64 v[6:7], v[6:7], 1, s[4:5]
	v_mul_u32_u24_e32 v1, 0x48, v137
	v_cndmask_b32_e64 v0, 0, 1, vcc
	v_cndmask_b32_e64 v0, v0, v2, s[38:39]
	v_and_b32_e32 v0, 1, v0
	v_cmp_eq_u32_e64 s[48:49], 1, v0
	v_or_b32_e32 v0, 8, v138
	v_cmp_le_u32_e32 vcc, v0, v137
	s_lshl_b32 s74, s20, 8
	v_lshl_add_u64 v[130:131], v[6:7], 0, v[196:197]
	v_cndmask_b32_e64 v2, 0, 1, vcc
	v_cmp_ge_u32_e32 vcc, v0, v137
	s_lshl_b32 s24, s20, 13
	s_bitset1_b32 s74, 15
	v_cndmask_b32_e64 v0, 0, 1, vcc
	v_cndmask_b32_e64 v0, v0, v2, s[38:39]
	v_and_b32_e32 v0, 1, v0
	v_cmp_eq_u32_e64 s[50:51], 1, v0
	v_or_b32_e32 v0, 9, v138
	v_cmp_le_u32_e32 vcc, v0, v137
	v_mul_u32_u24_e32 v139, 0x50, v137
	s_mov_b32 s31, 0
	v_cndmask_b32_e64 v2, 0, 1, vcc
	v_cmp_ge_u32_e32 vcc, v0, v137
	s_mov_b32 s20, -1
	v_lshlrev_b32_e32 v140, 1, v1
	v_cndmask_b32_e64 v0, 0, 1, vcc
	v_cndmask_b32_e64 v0, v0, v2, s[38:39]
	v_and_b32_e32 v0, 1, v0
	v_cmp_eq_u32_e64 s[52:53], 1, v0
	v_or_b32_e32 v0, 10, v138
	v_cmp_le_u32_e32 vcc, v0, v137
	v_lshlrev_b32_e32 v141, 1, v196
	s_waitcnt lgkmcnt(0)
	v_cndmask_b32_e64 v2, 0, 1, vcc
	v_cmp_ge_u32_e32 vcc, v0, v137
	s_barrier
; template <int DK>
; DI void scan_wg(const Params& p, char* smem, int grp, int dir, int hb) {
;     ...
;   f32x16 S[NT];
; #pragma unroll
;   for (int kt = 0; kt < NT; kt++)
; #pragma unroll
;     for (int e = 0; e < 16; e++) S[kt][e] = 0.f;
;   bf16x8 sq[QN], sk[QN], skt[QN], vn0, vn1;
;   float4 sd = make_float4(0.f, 0.f, 0.f, 0.f);
;   auto blk_of = [&](int step) { return dir ? (step < 8 ? 7 - step : 271 - step) : step; };
;   auto gload = [&](int step) {
;     const size_t pos0 = (size_t)blk_of(step) * 32;
; #pragma unroll
;     for (int i = 0; i < QN; i++) {
;       const int id = tid + i * 256;
;       sq[i] = *(const bf16x8*)(Qb + (pos0 + id / CPR) * DK + (id % CPR) * 8);
;       sk[i] = *(const bf16x8*)(Kb + (pos0 + id / CPR) * DK + (id % CPR) * 8);
;       skt[i] = *(const bf16x8*)(KTb + (size_t)blk_of(step) * DK * 32 + id * 8);
;     }
;     if (tid < DK / 4) sd = *(const float4*)(Db + (size_t)blk_of(step) * DK + tid * 4);
;     vn0 = *(const bf16x8*)(VTb + (size_t)blk_of(step) * 128 * 32);
;     vn1 = *(const bf16x8*)(VTb + (size_t)blk_of(step) * 128 * 32 + 16);
;   };
;     ...
;       const int pos0 = blk * 32;
;       int rbase, rstride;
;       if (pos0 < CTX) { rbase = NLAT + b * CTX + pos0; rstride = 1; }
;       else if (grp == 0) { rbase = b * SEQ + pos0 - CTX; rstride = 1; }
;       else { const int pp = pos0 - CTX; rbase = b * SEQ + (pp & 127) * 64 + (pp >> 7); rstride = 64; }
;       u16* orow = Ob + (size_t)(rbase + r * rstride) * D + 4 * h;
	s_nop 0
	v_cndmask_b32_e64 v0, 0, 1, vcc
	v_cndmask_b32_e64 v0, v0, v2, s[38:39]
	v_and_b32_e32 v0, 1, v0
	v_cmp_eq_u32_e64 s[54:55], 1, v0
	v_or_b32_e32 v0, 11, v138
	v_cmp_le_u32_e32 vcc, v0, v137
	s_nop 1
	v_cndmask_b32_e64 v2, 0, 1, vcc
	v_cmp_ge_u32_e32 vcc, v0, v137
	s_nop 1
	v_cndmask_b32_e64 v0, 0, 1, vcc
	v_cndmask_b32_e64 v0, v0, v2, s[38:39]
	v_and_b32_e32 v0, 1, v0
	v_cmp_eq_u32_e64 s[56:57], 1, v0
	v_or_b32_e32 v0, 16, v138
	v_cmp_le_u32_e32 vcc, v0, v137
	s_nop 1
	v_cndmask_b32_e64 v2, 0, 1, vcc
	v_cmp_ge_u32_e32 vcc, v0, v137
	s_nop 1
	v_cndmask_b32_e64 v0, 0, 1, vcc
	v_cndmask_b32_e64 v0, v0, v2, s[38:39]
	v_and_b32_e32 v0, 1, v0
	v_cmp_eq_u32_e64 s[58:59], 1, v0
	v_or_b32_e32 v0, 17, v138
	v_cmp_le_u32_e32 vcc, v0, v137
	s_nop 1
	v_cndmask_b32_e64 v2, 0, 1, vcc
	v_cmp_ge_u32_e32 vcc, v0, v137
	s_nop 1
	v_cndmask_b32_e64 v0, 0, 1, vcc
	v_cndmask_b32_e64 v0, v0, v2, s[38:39]
	v_and_b32_e32 v0, 1, v0
	v_cmp_eq_u32_e64 s[60:61], 1, v0
	v_or_b32_e32 v0, 18, v138
	v_cmp_le_u32_e32 vcc, v0, v137
	s_nop 1
	v_cndmask_b32_e64 v2, 0, 1, vcc
	v_cmp_ge_u32_e32 vcc, v0, v137
	s_nop 1
	v_cndmask_b32_e64 v0, 0, 1, vcc
	v_cndmask_b32_e64 v0, v0, v2, s[38:39]
	v_and_b32_e32 v0, 1, v0
	v_cmp_eq_u32_e64 s[62:63], 1, v0
	v_or_b32_e32 v0, 19, v138
	v_cmp_le_u32_e32 vcc, v0, v137
	s_nop 1
	v_cndmask_b32_e64 v2, 0, 1, vcc
	v_cmp_ge_u32_e32 vcc, v0, v137
	s_nop 1
	v_cndmask_b32_e64 v0, 0, 1, vcc
	v_cndmask_b32_e64 v0, v0, v2, s[38:39]
	v_and_b32_e32 v0, 1, v0
	v_cmp_eq_u32_e64 s[64:65], 1, v0
	v_or_b32_e32 v0, 24, v138
	v_cmp_le_u32_e32 vcc, v0, v137
	s_nop 1
	v_cndmask_b32_e64 v2, 0, 1, vcc
	v_cmp_ge_u32_e32 vcc, v0, v137
	s_nop 1
	v_cndmask_b32_e64 v0, 0, 1, vcc
	v_cndmask_b32_e64 v0, v0, v2, s[38:39]
	v_and_b32_e32 v0, 1, v0
	v_cmp_eq_u32_e64 s[66:67], 1, v0
	v_or_b32_e32 v0, 25, v138
	v_cmp_le_u32_e32 vcc, v0, v137
	s_nop 1
	v_cndmask_b32_e64 v2, 0, 1, vcc
	v_cmp_ge_u32_e32 vcc, v0, v137
	s_nop 1
	v_cndmask_b32_e64 v0, 0, 1, vcc
	v_cndmask_b32_e64 v0, v0, v2, s[38:39]
	v_and_b32_e32 v0, 1, v0
	v_cmp_eq_u32_e64 s[68:69], 1, v0
	v_or_b32_e32 v0, 26, v138
	v_cmp_le_u32_e32 vcc, v0, v137
	s_nop 1
	v_cndmask_b32_e64 v2, 0, 1, vcc
	v_cmp_ge_u32_e32 vcc, v0, v137
	s_nop 1
	v_cndmask_b32_e64 v0, 0, 1, vcc
	v_cndmask_b32_e64 v0, v0, v2, s[38:39]
	v_and_b32_e32 v0, 1, v0
	v_cmp_eq_u32_e64 s[70:71], 1, v0
	v_or_b32_e32 v0, 27, v138
	v_cmp_le_u32_e32 vcc, v0, v137
	s_nop 1
	v_cndmask_b32_e64 v2, 0, 1, vcc
	v_cmp_ge_u32_e32 vcc, v0, v137
	s_nop 1
	v_cndmask_b32_e64 v0, 0, 1, vcc
	v_cndmask_b32_e64 v0, v0, v2, s[38:39]
	v_and_b32_e32 v0, 1, v0
	v_cmp_eq_u32_e64 s[72:73], 1, v0
	v_mov_b32_e32 v0, 0
	v_mov_b32_e32 v1, v0
	v_mov_b32_e32 v2, v0
	v_mov_b32_e32 v3, v0
	v_mov_b32_e32 v4, v0
	v_mov_b32_e32 v5, v0
	v_mov_b32_e32 v6, v0
	v_mov_b32_e32 v7, v0
	v_mov_b32_e32 v8, v0
	v_mov_b32_e32 v9, v0
	v_mov_b32_e32 v10, v0
	v_mov_b32_e32 v11, v0
	v_mov_b32_e32 v12, v0
	v_mov_b32_e32 v13, v0
	v_mov_b32_e32 v14, v0
	v_mov_b32_e32 v15, v0
	v_mov_b32_e32 v16, v0
	v_mov_b32_e32 v17, v0
	v_mov_b32_e32 v18, v0
	v_mov_b32_e32 v19, v0
	v_mov_b32_e32 v20, v0
	v_mov_b32_e32 v21, v0
	v_mov_b32_e32 v22, v0
	v_mov_b32_e32 v23, v0
	v_mov_b32_e32 v24, v0
	v_mov_b32_e32 v25, v0
	v_mov_b32_e32 v26, v0
	v_mov_b32_e32 v27, v0
	v_mov_b32_e32 v28, v0
	v_mov_b32_e32 v29, v0
	v_mov_b32_e32 v30, v0
	v_mov_b32_e32 v31, v0
	v_mov_b32_e32 v96, v0
	v_mov_b32_e32 v97, v0
	v_mov_b32_e32 v98, v0
	v_mov_b32_e32 v99, v0
	v_mov_b32_e32 v100, v0
	v_mov_b32_e32 v101, v0
	v_mov_b32_e32 v103, v0
	v_mov_b32_e32 v119, v0
	v_mov_b32_e32 v142, v0
	v_mov_b32_e32 v143, v0
	v_mov_b32_e32 v144, v0
	v_mov_b32_e32 v145, v0
	v_mov_b32_e32 v146, v0
	v_mov_b32_e32 v147, v0
	v_mov_b32_e32 v148, v0
	v_mov_b32_e32 v102, v0
	v_mov_b32_e32 v104, v0
	v_mov_b32_e32 v105, v0
	v_mov_b32_e32 v106, v0
	v_mov_b32_e32 v107, v0
	v_mov_b32_e32 v109, v0
	v_mov_b32_e32 v111, v0
	v_mov_b32_e32 v113, v0
	v_mov_b32_e32 v108, v0
	v_mov_b32_e32 v110, v0
	v_mov_b32_e32 v112, v0
	v_mov_b32_e32 v114, v0
	v_mov_b32_e32 v115, v0
	v_mov_b32_e32 v116, v0
	v_mov_b32_e32 v117, v0
	v_mov_b32_e32 v118, v0
	v_lshl_add_u64 v[124:125], v[120:121], 1, v[124:125]
	v_lshl_add_u64 v[126:127], v[120:121], 1, v[126:127]
	v_and_b32_e32 v253, 0x3c0, v220
	v_lshlrev_b32_e32 v253, 4, v253
	v_sub_u32_e32 v136, v136, v253
	v_sub_u32_e32 v254, 0, v253
	v_ashrrev_i32_e32 v255, 31, v254
	v_lshl_add_u64 v[132:133], v[254:255], 0, v[132:133]
	s_mov_b32 s40, 0xffff
	s_mov_b32 s41, 0
	s_movk_i32 s26, 0x800
	v_lshlrev_b32_e32 v254, 1, v138
	v_mov_b32_e32 v255, 0
	v_lshl_add_u64 v[130:131], v[254:255], 0, v[130:131]
	s_mov_b32 s20, 1
	s_cmp_lt_u32 s20, 8
	s_cselect_b32 s21, 7, 0x10f
	s_sub_i32 s21, s21, s20
	s_and_b64 vcc, s[38:39], exec
	s_cselect_b32 s20, s20, s21
	s_lshl_b32 s82, s20, 8
	s_mov_b32 s83, 0
	s_lshl_b32 s20, s20, 12
	s_mov_b32 s21, 0
	v_lshl_add_u64 v[170:171], v[132:133], 0, s[82:83]
	s_mov_b64 exec, s[40:41]
	global_load_dwordx4 v[206:209], v[170:171], off
	s_mov_b64 exec, -1
	v_lshl_add_u64 v[142:143], v[124:125], 0, s[20:21]
	global_load_dwordx4 v[198:201], v[142:143], off
	v_lshl_add_u64 v[144:145], v[126:127], 0, s[20:21]
	global_load_dwordx4 v[202:205], v[144:145], off
	v_lshl_add_u64 v[146:147], v[128:129], 0, s[20:21]
	global_load_dwordx4 v[210:213], v[146:147], off
	s_mov_b32 s20, 2
	s_cmp_lt_u32 s20, 8
	s_cselect_b32 s21, 7, 0x10f
	s_sub_i32 s21, s21, s20
	s_and_b64 vcc, s[38:39], exec
	s_cselect_b32 s20, s20, s21
	s_lshl_b32 s82, s20, 8
	s_mov_b32 s83, 0
	s_lshl_b32 s20, s20, 12
	s_mov_b32 s21, 0
	v_lshl_add_u64 v[170:171], v[132:133], 0, s[82:83]
	s_mov_b64 exec, s[40:41]
	global_load_dwordx4 v[72:75], v[170:171], off
	s_mov_b64 exec, -1
	v_lshl_add_u64 v[142:143], v[124:125], 0, s[20:21]
	global_load_dwordx4 v[64:67], v[142:143], off
	v_lshl_add_u64 v[144:145], v[126:127], 0, s[20:21]
	global_load_dwordx4 v[68:71], v[144:145], off
	v_lshl_add_u64 v[146:147], v[128:129], 0, s[20:21]
	global_load_dwordx4 v[76:79], v[146:147], off
	s_mov_b32 s4, 1
	s_cmp_lt_u32 s4, 8
	s_cselect_b32 s5, 7, 0x10f
	s_sub_i32 s5, s5, s4
	s_and_b64 vcc, s[38:39], exec
	s_cselect_b32 s4, s4, s5
	s_lshl_b32 s4, s4, 13
	s_mov_b32 s5, 0
	v_lshl_add_u64 v[218:219], v[122:123], 0, s[4:5]
	global_load_dwordx4 v[214:217], v[218:219], off
	global_load_dwordx4 v[230:233], v[218:219], off offset:32
	s_waitcnt vmcnt(0)

; template <int DK>
; DI void scan_wg(const Params& p, char* smem, int grp, int dir, int hb) {
;     ...
;   auto gload = [&](int step) {
;     const size_t pos0 = (size_t)blk_of(step) * 32;
; #pragma unroll
;     for (int i = 0; i < QN; i++) {
;       const int id = tid + i * 256;
;       sq[i] = *(const bf16x8*)(Qb + (pos0 + id / CPR) * DK + (id % CPR) * 8);
;       sk[i] = *(const bf16x8*)(Kb + (pos0 + id / CPR) * DK + (id % CPR) * 8);
;       skt[i] = *(const bf16x8*)(KTb + (size_t)blk_of(step) * DK * 32 + id * 8);
;     }
;     if (tid < DK / 4) sd = *(const float4*)(Db + (size_t)blk_of(step) * DK + tid * 4);
;     vn0 = *(const bf16x8*)(VTb + (size_t)blk_of(step) * 128 * 32);
;     vn1 = *(const bf16x8*)(VTb + (size_t)blk_of(step) * 128 * 32 + 16);
;   };
;   auto lstore = [&](int buf) {
;     char* base = smem + buf * BUFB;
; #pragma unroll
;     for (int i = 0; i < QN; i++) {
;       const int id = tid + i * 256;
;       *(bf16x8*)(base + ((id / CPR) * QS + (id % CPR) * 8) * 2) = sq[i];
;       *(bf16x8*)(base + OFF_K + ((id / CPR) * QS + (id % CPR) * 8) * 2) = sk[i];
;       *(bf16x8*)(base + OFF_KT + ((id >> 2) * KTS + (id & 3) * 8) * 2) = skt[i];
;     }
;     if (tid < DK / 4) *(float4*)(base + OFF_D + tid * 16) = sd;
;   };
.Lgs_lv_done:
	s_add_i32 s20, s31, 3
	s_min_u32 s20, s20, 0x107
	s_cmp_lt_u32 s20, 8
	s_cselect_b32 s21, 7, 0x10f
	s_sub_i32 s21, s21, s20
	s_and_b64 vcc, s[38:39], exec
	s_cselect_b32 s20, s20, s21
	s_lshl_b32 s82, s20, 8
	s_mov_b32 s83, 0
	s_lshl_b32 s20, s20, 12
	s_mov_b32 s21, 0
	s_waitcnt vmcnt(12)
	s_bitcmp1_b32 s31, 0
	s_cbranch_scc1 .Lgs_wl_odd
	v_add_u32_e32 v148, s1, v134
	v_add_u32_e32 v149, s1, v135
	v_add_u32_e32 v253, s1, v136
	ds_write_b128 v148, v[198:201]
	ds_write_b128 v148, v[202:205] offset:4608
	ds_write_b128 v149, v[210:213] offset:9216
	s_mov_b64 exec, s[40:41]
	ds_write_b128 v253, v[206:209] offset:14336
	s_mov_b64 exec, -1
	v_lshl_add_u64 v[170:171], v[132:133], 0, s[82:83]
	s_mov_b64 exec, s[40:41]
	global_load_dwordx4 v[206:209], v[170:171], off
	s_mov_b64 exec, -1
	v_lshl_add_u64 v[142:143], v[124:125], 0, s[20:21]
	global_load_dwordx4 v[198:201], v[142:143], off
	v_lshl_add_u64 v[144:145], v[126:127], 0, s[20:21]
	global_load_dwordx4 v[202:205], v[144:145], off
	v_lshl_add_u64 v[146:147], v[128:129], 0, s[20:21]
	global_load_dwordx4 v[210:213], v[146:147], off
	s_branch .Lgs_wl_done

; template <int DK>
; DI void scan_wg(const Params& p, char* smem, int grp, int dir, int hb) {
;     ...
;     const u16* Qs = (const u16*)base + r * QS + h * 8;
;     const u16* Ks = (const u16*)(base + OFF_K) + r * QS + h * 8;
;     const u16* KTs = (const u16*)(base + OFF_KT) + r * KTS + h * 8;
;     const float* Ds = (const float*)(base + OFF_D) + 4 * h;
;     bf16x8 qf[NF];
;     f32x16 P0, P1;
; #pragma unroll
;     for (int e = 0; e < 16; e++) { P0[e] = 0.f; P1[e] = 0.f; }
; #pragma unroll
;     for (int f = 0; f < NF; f += 2) {
;       qf[f] = *(const bf16x8*)(Qs + f * 16);
;       qf[f + 1] = *(const bf16x8*)(Qs + f * 16 + 16);
;       P0 = MFMA32(*(const bf16x8*)(Ks + f * 16), qf[f], P0);
;       P1 = MFMA32(*(const bf16x8*)(Ks + f * 16 + 16), qf[f + 1], P1);
;     }
; #pragma unroll
;     for (int e = 0; e < 16; e++) {
;       const int s = crow(e, h);
;       const bool keep = dir ? (s >= r) : (s <= r);
;       P0[e] = keep ? P0[e] + P1[e] : 0.f;
;     }
;     f32x16 oA, oB;
; #pragma unroll
;     for (int e = 0; e < 16; e++) { oA[e] = 0.f; oB[e] = 0.f; }
;     oA = MFMA32(vf0, pack_frag(P0, 0), oA);
;     oA = MFMA32(vf1, pack_frag(P0, 1), oA);
; #pragma unroll
;     for (int kt = 0; kt < NT; kt++) {
;       if (kt & 1) {
;         oA = MFMA32(pack_frag(S[kt], 0), qf[kt * 2], oA);
;         oA = MFMA32(pack_frag(S[kt], 1), qf[kt * 2 + 1], oA);
;       } else {
;         oB = MFMA32(pack_frag(S[kt], 0), qf[kt * 2], oB);
;         oB = MFMA32(pack_frag(S[kt], 1), qf[kt * 2 + 1], oB);
;       }
;     }
; #pragma unroll
;     for (int kt = 0; kt < NT; kt++) {
;       S[kt] = MFMA32(*(const bf16x8*)(KTs + kt * 32 * KTS), vf0, S[kt]);
;       S[kt] = MFMA32(*(const bf16x8*)(KTs + kt * 32 * KTS + 16), vf1, S[kt]);
; #pragma unroll
;       for (int g = 0; g < 4; g++) {
;         const float4 dv = *(const float4*)(Ds + kt * 32 + 8 * g);
;         S[kt][4 * g + 0] *= dv.x; S[kt][4 * g + 1] *= dv.y; S[kt][4 * g + 2] *= dv.z; S[kt][4 * g + 3] *= dv.w;
;       }
;     }
;     {
;       const int pos0 = blk * 32;
;       int rbase, rstride;
;       if (pos0 < CTX) { rbase = NLAT + b * CTX + pos0; rstride = 1; }
;       else if (grp == 0) { rbase = b * SEQ + pos0 - CTX; rstride = 1; }
;       else { const int pp = pos0 - CTX; rbase = b * SEQ + (pp & 127) * 64 + (pp >> 7); rstride = 64; }
;       u16* orow = Ob + (size_t)(rbase + r * rstride) * D + 4 * h;
.Lgs_wl_done:
	v_add3_u32 v166, s0, v140, v141
	v_add3_u32 v167, s0, v139, v141
	v_lshl_or_b32 v168, v138, 2, s0
	ds_read_b128 v[172:175], v166 offset:4608
	ds_read_b128 v[176:179], v166
	ds_read_b128 v[180:183], v166 offset:4640
	ds_read_b128 v[184:187], v166 offset:32
	ds_read_b128 v[188:191], v166 offset:4672
	ds_read_b128 v[192:195], v166 offset:64
	ds_read_b128 v[142:145], v166 offset:4704
	ds_read_b128 v[146:149], v166 offset:96
	s_waitcnt lgkmcnt(6)
	v_mfma_f32_32x32x16_bf16 v[32:47], v[172:175], v[176:179], 0
	v_cvt_pk_bf16_f32 v48, v0, v1
	v_cvt_pk_bf16_f32 v49, v2, v3
	v_cvt_pk_bf16_f32 v50, v4, v5
	v_cvt_pk_bf16_f32 v51, v6, v7
	s_waitcnt lgkmcnt(4)
	v_mfma_f32_32x32x16_bf16 v[32:47], v[180:183], v[184:187], v[32:47]
	v_cvt_pk_bf16_f32 v52, v8, v9
	v_cvt_pk_bf16_f32 v53, v10, v11
	v_cvt_pk_bf16_f32 v54, v12, v13
	v_cvt_pk_bf16_f32 v55, v14, v15
	s_waitcnt lgkmcnt(2)
	v_mfma_f32_32x32x16_bf16 v[32:47], v[188:191], v[192:195], v[32:47]
	ds_read_b128 v[150:153], v167 offset:9216
	ds_read_b128 v[154:157], v167 offset:9248
	ds_read_b128 v[158:161], v167 offset:11776
	ds_read_b128 v[162:165], v167 offset:11808
	v_cvt_pk_bf16_f32 v56, v16, v17
	v_cvt_pk_bf16_f32 v57, v18, v19
	v_cvt_pk_bf16_f32 v58, v20, v21
	v_cvt_pk_bf16_f32 v59, v22, v23
	s_waitcnt lgkmcnt(4)
	v_mfma_f32_32x32x16_bf16 v[32:47], v[142:145], v[146:149], v[32:47]
	v_cvt_pk_bf16_f32 v60, v24, v25
	v_cvt_pk_bf16_f32 v61, v26, v27
	v_cvt_pk_bf16_f32 v62, v28, v29
	v_cvt_pk_bf16_f32 v63, v30, v31
	s_waitcnt lgkmcnt(3)
	v_mfma_f32_32x32x16_bf16 v[0:15], v[150:153], v[84:87], v[0:15]
	ds_read_b128 v[96:99], v168 offset:14336
	ds_read_b128 v[100:103], v168 offset:14368
	ds_read_b128 v[104:107], v168 offset:14400
	ds_read_b128 v[108:111], v168 offset:14432
	ds_read_b128 v[112:115], v168 offset:14464
	ds_read_b128 v[116:119], v168 offset:14496
	ds_read_b128 v[234:237], v168 offset:14528
	ds_read_b128 v[238:241], v168 offset:14560
	s_waitcnt lgkmcnt(10)
	v_mfma_f32_32x32x16_bf16 v[0:15], v[154:157], v[80:83], v[0:15]
	v_cndmask_b32_e64 v32, 0, v32, s[42:43]
	v_cndmask_b32_e64 v33, 0, v33, s[44:45]
	v_cndmask_b32_e64 v34, 0, v34, s[46:47]
	v_cndmask_b32_e64 v35, 0, v35, s[48:49]
	v_cndmask_b32_e64 v36, 0, v36, s[50:51]
	v_cndmask_b32_e64 v37, 0, v37, s[52:53]
	s_waitcnt lgkmcnt(9)
	v_mfma_f32_32x32x16_bf16 v[16:31], v[158:161], v[84:87], v[16:31]
	v_cndmask_b32_e64 v38, 0, v38, s[54:55]
	v_cndmask_b32_e64 v39, 0, v39, s[56:57]
	v_cvt_pk_bf16_f32 v242, v32, v33
	v_cvt_pk_bf16_f32 v243, v34, v35
	v_cvt_pk_bf16_f32 v244, v36, v37
	v_cvt_pk_bf16_f32 v245, v38, v39
	v_cndmask_b32_e64 v40, 0, v40, s[58:59]
	v_cndmask_b32_e64 v41, 0, v41, s[60:61]
	v_cndmask_b32_e64 v42, 0, v42, s[62:63]
	s_waitcnt lgkmcnt(8)
	v_mfma_f32_32x32x16_bf16 v[16:31], v[162:165], v[80:83], v[16:31]
	ds_read_b128 v[172:175], v166
	ds_read_b128 v[176:179], v166 offset:32
	ds_read_b128 v[180:183], v166 offset:64
	ds_read_b128 v[184:187], v166 offset:96
	v_cndmask_b32_e64 v43, 0, v43, s[64:65]
	v_cndmask_b32_e64 v44, 0, v44, s[66:67]
	v_cndmask_b32_e64 v45, 0, v45, s[68:69]
	v_cndmask_b32_e64 v46, 0, v46, s[70:71]
	v_cndmask_b32_e64 v47, 0, v47, s[72:73]
	v_cvt_pk_bf16_f32 v246, v40, v41
	v_cvt_pk_bf16_f32 v247, v42, v43
	v_cvt_pk_bf16_f32 v248, v44, v45
	v_cvt_pk_bf16_f32 v249, v46, v47
	v_mfma_f32_32x32x16_bf16 v[32:47], v[84:87], v[242:245], 0
	s_waitcnt lgkmcnt(10)
	v_mul_f32_e32 v0, v0, v96
	v_mul_f32_e32 v1, v1, v97
	v_mul_f32_e32 v2, v2, v98
	v_mul_f32_e32 v3, v3, v99
	v_mul_f32_e32 v4, v4, v100
	v_mul_f32_e32 v5, v5, v101
	v_mul_f32_e32 v6, v6, v102
	v_mul_f32_e32 v7, v7, v103
	v_mfma_f32_32x32x16_bf16 v[32:47], v[80:83], v[246:249], v[32:47]
	s_waitcnt lgkmcnt(8)
	v_mul_f32_e32 v8, v8, v104
	v_mul_f32_e32 v9, v9, v105
	v_mul_f32_e32 v10, v10, v106
	v_mul_f32_e32 v11, v11, v107
	v_mul_f32_e32 v12, v12, v108
	v_mul_f32_e32 v13, v13, v109
	v_mul_f32_e32 v14, v14, v110
	v_mul_f32_e32 v15, v15, v111
	s_waitcnt lgkmcnt(3)
	v_mfma_f32_32x32x16_bf16 v[32:47], v[48:51], v[172:175], v[32:47]
	v_mul_f32_e32 v16, v16, v112
	v_mul_f32_e32 v17, v17, v113
	v_mul_f32_e32 v18, v18, v114
	v_mul_f32_e32 v19, v19, v115
	v_mul_f32_e32 v20, v20, v116
	v_mul_f32_e32 v21, v21, v117
	v_mul_f32_e32 v22, v22, v118
	v_mul_f32_e32 v23, v23, v119
	s_waitcnt lgkmcnt(2)
	v_mfma_f32_32x32x16_bf16 v[32:47], v[52:55], v[176:179], v[32:47]
	v_mul_f32_e32 v24, v24, v234
	v_mul_f32_e32 v25, v25, v235
	v_mul_f32_e32 v26, v26, v236
	v_mul_f32_e32 v27, v27, v237
	v_mul_f32_e32 v28, v28, v238
	v_mul_f32_e32 v29, v29, v239
	v_mul_f32_e32 v30, v30, v240
	v_mul_f32_e32 v31, v31, v241
	s_waitcnt lgkmcnt(1)
	v_mfma_f32_32x32x16_bf16 v[32:47], v[56:59], v[180:183], v[32:47]
	s_mov_b32 s4, s31
	s_cmp_lt_u32 s4, 8
	s_cselect_b32 s5, 7, 0x10f
	s_sub_i32 s5, s5, s4
	s_and_b64 vcc, s[38:39], exec
	s_cselect_b32 s4, s4, s5
	s_lshl_b32 s5, s4, 5
	s_lshl_b32 s27, s4, 11
	s_and_b32 s27, s27, 0x1800
	s_or_b32 s27, s27, s24
	s_add_i32 s21, s5, 0xffffff00
	s_lshr_b32 s21, s21, 7
	s_add_i32 s27, s27, s21
	s_add_i32 s21, s74, s5
	s_cmp_gt_i32 s4, 7
	s_cselect_b32 s21, s27, s21
	s_cselect_b32 s27, 64, 1
	v_mov_b32_e32 v253, s21
	s_waitcnt lgkmcnt(0)
	v_mfma_f32_32x32x16_bf16 v[32:47], v[60:63], v[184:187], v[32:47]
	v_mad_u32_u24 v253, s27, v137, v253
	v_mad_u64_u32 v[254:255], s[20:21], v253, s26, v[130:131]
	s_waitcnt vmcnt(12)
	s_bitcmp1_b32 s31, 0
	s_cbranch_scc1 .Lgs_cp_odd
	v_mov_b64_e32 v[84:85], v[214:215]
	v_mov_b64_e32 v[86:87], v[216:217]
	v_mov_b64_e32 v[80:81], v[230:231]
	v_mov_b64_e32 v[82:83], v[232:233]
	s_branch .Lgs_cp_done

; DI u32 pack2(float a, float b) { f32x2v v = {a, b}; return __builtin_bit_cast(u32, __builtin_convertvector(v, bf16x2v)); }
; template <int DK>
; DI void scan_wg(const Params& p, char* smem, int grp, int dir, int hb) {
;     ...
;       u16* orow = Ob + (size_t)(rbase + r * rstride) * D + 4 * h;
; #pragma unroll
;       for (int g = 0; g < 4; g++)
;         *(uint2*)(orow + 8 * g) = make_uint2(pack2(oA[4 * g] + oB[4 * g], oA[4 * g + 1] + oB[4 * g + 1]),
;                                              pack2(oA[4 * g + 2] + oB[4 * g + 2], oA[4 * g + 3] + oB[4 * g + 3]));
.Lgs_cp_done:
	s_add_i32 s31, s31, 1
	s_nop 3
	v_cvt_pk_bf16_f32 v172, v32, v33
	v_cvt_pk_bf16_f32 v173, v34, v35
	v_cvt_pk_bf16_f32 v174, v36, v37
	v_cvt_pk_bf16_f32 v175, v38, v39
	v_cvt_pk_bf16_f32 v176, v40, v41
	v_cvt_pk_bf16_f32 v177, v42, v43
	v_cvt_pk_bf16_f32 v178, v44, v45
	v_cvt_pk_bf16_f32 v179, v46, v47
	s_nop 1
	v_permlane32_swap_b32_e32 v172, v174
	v_permlane32_swap_b32_e32 v173, v175
	v_permlane32_swap_b32_e32 v176, v178
	v_permlane32_swap_b32_e32 v177, v179
	global_store_dwordx4 v[254:255], v[172:175], off offset:1024
	global_store_dwordx4 v[254:255], v[176:179], off offset:1056
	s_cmpk_eq_i32 s31, 0x108
	s_waitcnt lgkmcnt(0)
	s_barrier
	s_cbranch_scc0 .Lgs_top
	s_waitcnt vmcnt(0)
	s_branch .LBB0_582

; DI int crow(int i, int h) { return (i & 3) + 8 * (i >> 2) + 4 * h; }
; template <int DK>
; DI void scan_wg(const Params& p, char* smem, int grp, int dir, int hb) {
;     ...
;   auto lstore = [&](int buf) {
;     char* base = smem + buf * BUFB;
; #pragma unroll
;     for (int i = 0; i < QN; i++) {
;       const int id = tid + i * 256;
;       *(bf16x8*)(base + ((id / CPR) * QS + (id % CPR) * 8) * 2) = sq[i];
;       *(bf16x8*)(base + OFF_K + ((id / CPR) * QS + (id % CPR) * 8) * 2) = sk[i];
;       *(bf16x8*)(base + OFF_KT + ((id >> 2) * KTS + (id & 3) * 8) * 2) = skt[i];
;     }
;     if (tid < DK / 4) *(float4*)(base + OFF_D + tid * 16) = sd;
;   };
;   __builtin_amdgcn_s_setprio(3);
;   __syncthreads();
;   gload(0);
;   lstore(0);
;   bf16x8 vf0 = vn0, vf1 = vn1;
;   __syncthreads();
;     ...
;     for (int e = 0; e < 16; e++) {
;       const int s = crow(e, h);
;       const bool keep = dir ? (s >= r) : (s <= r);
;       P0[e] = keep ? P0[e] + P1[e] : 0.f;
;     }
.LBB0_586:
	s_or_b64 exec, exec, s[4:5]
	v_ashrrev_i32_e32 v13, 1, v10
	s_movk_i32 s20, 0xffe0
	v_readlane_b32 s4, v251, 44
	v_bfi_b32 v14, s20, v13, v10
	s_add_u32 s4, s4, s75
	v_readlane_b32 s5, v251, 45
	v_lshlrev_b32_e32 v14, 5, v14
	v_bfe_u32 v12, v10, 5, 1
	s_addc_u32 s5, s5, 0
	v_ashrrev_i32_e32 v15, 31, v14
	v_lshl_add_u64 v[14:15], v[14:15], 1, s[4:5]
	v_lshlrev_b32_e32 v196, 4, v12
	v_lshl_add_u64 v[206:207], v[14:15], 0, v[196:197]
	v_lshl_add_u64 v[14:15], v[206:207], 0, s[24:25]
	global_load_dwordx4 v[128:131], v[14:15], off
	global_load_dwordx4 v[124:127], v[14:15], off offset:32
	s_movk_i32 s4, 0x110
	v_mul_lo_u32 v4, v4, s4
	v_lshl_add_u32 v230, v5, 4, v4
	v_lshrrev_b32_e32 v4, 2, v10
	v_mul_lo_u32 v4, v4, 40
	v_and_b32_e32 v5, 24, v200
	v_add_lshl_u32 v231, v4, v5, 1
	v_mul_lo_u32 v4, v8, s4
	v_lshl_add_u32 v232, v9, 4, v4
	v_lshrrev_b32_e32 v4, 2, v11
	v_mul_lo_u32 v4, v4, 40
	v_add_lshl_u32 v233, v4, v5, 1
	v_lshlrev_b32_e32 v234, 4, v10
	s_waitcnt vmcnt(7)
	ds_write_b128 v230, v[96:99]
	s_waitcnt vmcnt(6)
	ds_write_b128 v230, v[100:103] offset:8704
	s_waitcnt vmcnt(5)
	ds_write_b128 v231, v[104:107] offset:17408
	s_waitcnt vmcnt(4)
	ds_write_b128 v232, v[108:111]
	s_waitcnt vmcnt(3)
	ds_write_b128 v232, v[116:119] offset:8704
	s_waitcnt vmcnt(2)
	ds_write_b128 v233, v[120:123] offset:17408
	s_and_saveexec_b64 s[4:5], s[40:41]
	ds_write_b128 v234, v[112:115] offset:27648
	s_or_b64 exec, exec, s[4:5]
	v_and_b32_e32 v235, 31, v10
	v_lshlrev_b32_e32 v236, 2, v12
	v_cmp_le_u32_e32 vcc, v236, v235
	v_lshl_add_u64 v[208:209], s[44:45], 0, v[0:1]
	v_lshl_add_u64 v[210:211], s[0:1], 0, v[0:1]
	v_cndmask_b32_e64 v1, 0, 1, vcc
	v_cmp_ge_u32_e32 vcc, v236, v235
	v_lshl_add_u64 v[212:213], s[44:45], 0, v[2:3]
	v_lshl_add_u64 v[214:215], s[0:1], 0, v[2:3]
	v_cndmask_b32_e64 v2, 0, 1, vcc
	v_cndmask_b32_e64 v1, v2, v1, s[38:39]
	v_and_b32_e32 v1, 1, v1
	v_lshl_add_u64 v[218:219], v[6:7], 2, s[42:43]
	v_cmp_eq_u32_e64 s[42:43], 1, v1
	v_or_b32_e32 v1, 1, v236
	v_cmp_lt_u32_e32 vcc, v236, v235
	s_lshr_b32 s20, s82, 2
	s_add_u32 s4, s14, s33
	v_cndmask_b32_e64 v2, 0, 1, vcc
	v_cmp_ge_u32_e32 vcc, v1, v235
	s_addc_u32 s5, s15, 0
	s_lshl_b32 s21, s37, 8
	v_cndmask_b32_e64 v1, 0, 1, vcc
	v_cndmask_b32_e64 v1, v1, v2, s[38:39]
	v_and_b32_e32 v1, 1, v1
	v_cmp_eq_u32_e64 s[44:45], 1, v1
	v_or_b32_e32 v1, 2, v236
	v_cmp_le_u32_e32 vcc, v1, v235
	s_and_b32 s21, s21, 0x300
	v_and_b32_e32 v4, 0xffffffe0, v13
	v_cndmask_b32_e64 v2, 0, 1, vcc
	v_cmp_ge_u32_e32 vcc, v1, v235
	s_add_u32 s4, s4, s21
	v_ashrrev_i32_e32 v5, 31, v4
	v_cndmask_b32_e64 v1, 0, 1, vcc
	v_cndmask_b32_e64 v1, v1, v2, s[38:39]
	v_and_b32_e32 v1, 1, v1
	v_cmp_eq_u32_e64 s[46:47], 1, v1
	v_or_b32_e32 v1, 3, v236
	v_cmp_le_u32_e32 vcc, v1, v235
	s_addc_u32 s5, s5, 0
	v_lshlrev_b32_e32 v196, 3, v12
	v_cndmask_b32_e64 v2, 0, 1, vcc
	v_cmp_ge_u32_e32 vcc, v1, v235
	v_lshl_add_u64 v[4:5], v[4:5], 1, s[4:5]
	v_mul_u32_u24_e32 v0, 0x88, v235
	v_cndmask_b32_e64 v1, 0, 1, vcc
	v_cndmask_b32_e64 v1, v1, v2, s[38:39]
	v_and_b32_e32 v1, 1, v1
	v_cmp_eq_u32_e64 s[48:49], 1, v1
	v_or_b32_e32 v1, 8, v236
	v_cmp_le_u32_e32 vcc, v1, v235
	s_lshl_b32 s24, s20, 13
	s_lshl_b32 s33, s20, 8
	v_cndmask_b32_e64 v2, 0, 1, vcc
	v_cmp_ge_u32_e32 vcc, v1, v235
	v_mov_b32_e32 v172, 0
	v_lshl_add_u64 v[216:217], v[4:5], 0, v[196:197]
	v_cndmask_b32_e64 v1, 0, 1, vcc
	v_cndmask_b32_e64 v1, v1, v2, s[38:39]
	v_and_b32_e32 v1, 1, v1
	v_cmp_eq_u32_e64 s[50:51], 1, v1
	v_or_b32_e32 v1, 9, v236
	v_cmp_le_u32_e32 vcc, v1, v235
	s_addk_i32 s24, 0xff00
	s_bitset1_b32 s33, 15
	v_cndmask_b32_e64 v2, 0, 1, vcc
	v_cmp_ge_u32_e32 vcc, v1, v235
	v_mul_u32_u24_e32 v237, 0x50, v235
	s_mov_b32 s30, 0
	v_cndmask_b32_e64 v1, 0, 1, vcc
	v_cndmask_b32_e64 v1, v1, v2, s[38:39]
	v_and_b32_e32 v1, 1, v1
	v_cmp_eq_u32_e64 s[52:53], 1, v1
	v_or_b32_e32 v1, 10, v236
	v_cmp_le_u32_e32 vcc, v1, v235
	s_mov_b32 s75, -1
	v_lshlrev_b32_e32 v238, 1, v0
	v_cndmask_b32_e64 v2, 0, 1, vcc
	v_cmp_ge_u32_e32 vcc, v1, v235
	v_lshlrev_b32_e32 v196, 1, v196
	v_mov_b32_e32 v173, v172
	v_cndmask_b32_e64 v1, 0, 1, vcc
	v_cndmask_b32_e64 v1, v1, v2, s[38:39]
	v_and_b32_e32 v1, 1, v1
	v_cmp_eq_u32_e64 s[54:55], 1, v1
	v_or_b32_e32 v1, 11, v236
	v_cmp_le_u32_e32 vcc, v1, v235
	v_mov_b32_e32 v0, v172
	v_mov_b32_e32 v3, v172
	v_cndmask_b32_e64 v2, 0, 1, vcc
	v_cmp_ge_u32_e32 vcc, v1, v235
	v_mov_b32_e32 v4, v172
	v_mov_b32_e32 v5, v172
	v_cndmask_b32_e64 v1, 0, 1, vcc
	v_cndmask_b32_e64 v1, v1, v2, s[38:39]
	v_and_b32_e32 v1, 1, v1
	v_cmp_eq_u32_e64 s[56:57], 1, v1
	v_or_b32_e32 v1, 16, v236
	v_cmp_le_u32_e32 vcc, v1, v235
	v_mov_b32_e32 v6, v172
	v_mov_b32_e32 v7, v172
	v_cndmask_b32_e64 v2, 0, 1, vcc
	v_cmp_ge_u32_e32 vcc, v1, v235
	v_mov_b32_e32 v8, v172
	v_mov_b32_e32 v9, v172
	v_cndmask_b32_e64 v1, 0, 1, vcc
	v_cndmask_b32_e64 v1, v1, v2, s[38:39]
	v_and_b32_e32 v1, 1, v1
	v_cmp_eq_u32_e64 s[58:59], 1, v1
	v_or_b32_e32 v1, 17, v236
	v_cmp_le_u32_e32 vcc, v1, v235
	v_mov_b32_e32 v10, v172
	v_mov_b32_e32 v11, v172
	v_cndmask_b32_e64 v2, 0, 1, vcc
	v_cmp_ge_u32_e32 vcc, v1, v235
	v_mov_b32_e32 v12, v172
	v_mov_b32_e32 v13, v172
	v_cndmask_b32_e64 v1, 0, 1, vcc
	v_cndmask_b32_e64 v1, v1, v2, s[38:39]
	v_and_b32_e32 v1, 1, v1
	v_cmp_eq_u32_e64 s[60:61], 1, v1
	v_or_b32_e32 v1, 18, v236
	v_cmp_le_u32_e32 vcc, v1, v235
	v_mov_b32_e32 v14, v172
	v_mov_b32_e32 v15, v172
	v_cndmask_b32_e64 v2, 0, 1, vcc
	v_cmp_ge_u32_e32 vcc, v1, v235
	v_mov_b32_e32 v156, v172
	v_mov_b32_e32 v157, v172
	v_cndmask_b32_e64 v1, 0, 1, vcc
	v_cndmask_b32_e64 v1, v1, v2, s[38:39]
	v_and_b32_e32 v1, 1, v1
	v_cmp_eq_u32_e64 s[62:63], 1, v1
	v_or_b32_e32 v1, 19, v236
	v_cmp_le_u32_e32 vcc, v1, v235
; template <int DK>
; DI void scan_wg(const Params& p, char* smem, int grp, int dir, int hb) {
;     ...
;   f32x16 S[NT];
; #pragma unroll
;   for (int kt = 0; kt < NT; kt++)
; #pragma unroll
;     for (int e = 0; e < 16; e++) S[kt][e] = 0.f;
;   bf16x8 sq[QN], sk[QN], skt[QN], vn0, vn1;
;   float4 sd = make_float4(0.f, 0.f, 0.f, 0.f);
;   auto blk_of = [&](int step) { return dir ? (step < 8 ? 7 - step : 271 - step) : step; };
;   auto gload = [&](int step) {
;     const size_t pos0 = (size_t)blk_of(step) * 32;
; #pragma unroll
;     for (int i = 0; i < QN; i++) {
;       const int id = tid + i * 256;
;       sq[i] = *(const bf16x8*)(Qb + (pos0 + id / CPR) * DK + (id % CPR) * 8);
;       sk[i] = *(const bf16x8*)(Kb + (pos0 + id / CPR) * DK + (id % CPR) * 8);
;       skt[i] = *(const bf16x8*)(KTb + (size_t)blk_of(step) * DK * 32 + id * 8);
;     }
;     if (tid < DK / 4) sd = *(const float4*)(Db + (size_t)blk_of(step) * DK + tid * 4);
;     vn0 = *(const bf16x8*)(VTb + (size_t)blk_of(step) * 128 * 32);
;     vn1 = *(const bf16x8*)(VTb + (size_t)blk_of(step) * 128 * 32 + 16);
;   };
;   auto lstore = [&](int buf) {
;     char* base = smem + buf * BUFB;
; #pragma unroll
;     for (int i = 0; i < QN; i++) {
;       const int id = tid + i * 256;
;       *(bf16x8*)(base + ((id / CPR) * QS + (id % CPR) * 8) * 2) = sq[i];
;       *(bf16x8*)(base + OFF_K + ((id / CPR) * QS + (id % CPR) * 8) * 2) = sk[i];
;       *(bf16x8*)(base + OFF_KT + ((id >> 2) * KTS + (id & 3) * 8) * 2) = skt[i];
;     }
;     if (tid < DK / 4) *(float4*)(base + OFF_D + tid * 16) = sd;
;   };
;   __builtin_amdgcn_s_setprio(3);
;   __syncthreads();
;   gload(0);
;   lstore(0);
;   bf16x8 vf0 = vn0, vf1 = vn1;
;   __syncthreads();
; #pragma unroll 1
;   for (int step = 0; step < NBLK; step++) {
;     const int blk = blk_of(step);
;     if (step + 1 < NBLK) gload(step + 1);
;     ...
;       u16* orow = Ob + (size_t)(rbase + r * rstride) * D + 4 * h;
	v_mov_b32_e32 v16, v172
	v_mov_b32_e32 v17, v172
	v_cndmask_b32_e64 v2, 0, 1, vcc
	v_cmp_ge_u32_e32 vcc, v1, v235
	v_mov_b32_e32 v18, v172
	v_mov_b32_e32 v19, v172
	v_cndmask_b32_e64 v1, 0, 1, vcc
	v_cndmask_b32_e64 v1, v1, v2, s[38:39]
	v_and_b32_e32 v1, 1, v1
	v_cmp_eq_u32_e64 s[64:65], 1, v1
	v_or_b32_e32 v1, 24, v236
	v_cmp_le_u32_e32 vcc, v1, v235
	v_mov_b32_e32 v20, v172
	v_mov_b32_e32 v21, v172
	v_cndmask_b32_e64 v2, 0, 1, vcc
	v_cmp_ge_u32_e32 vcc, v1, v235
	v_mov_b32_e32 v22, v172
	v_mov_b32_e32 v23, v172
	v_cndmask_b32_e64 v1, 0, 1, vcc
	v_cndmask_b32_e64 v1, v1, v2, s[38:39]
	v_and_b32_e32 v1, 1, v1
	v_cmp_eq_u32_e64 s[66:67], 1, v1
	v_or_b32_e32 v1, 25, v236
	v_cmp_le_u32_e32 vcc, v1, v235
	v_mov_b32_e32 v24, v172
	v_mov_b32_e32 v25, v172
	v_cndmask_b32_e64 v2, 0, 1, vcc
	v_cmp_ge_u32_e32 vcc, v1, v235
	v_mov_b32_e32 v26, v172
	v_mov_b32_e32 v27, v172
	v_cndmask_b32_e64 v1, 0, 1, vcc
	v_cndmask_b32_e64 v1, v1, v2, s[38:39]
	v_and_b32_e32 v1, 1, v1
	v_cmp_eq_u32_e64 s[68:69], 1, v1
	v_or_b32_e32 v1, 26, v236
	v_cmp_le_u32_e32 vcc, v1, v235
	v_mov_b32_e32 v28, v172
	v_mov_b32_e32 v29, v172
	v_cndmask_b32_e64 v2, 0, 1, vcc
	v_cmp_ge_u32_e32 vcc, v1, v235
	v_mov_b32_e32 v30, v172
	v_mov_b32_e32 v31, v172
	v_cndmask_b32_e64 v1, 0, 1, vcc
	v_cndmask_b32_e64 v1, v1, v2, s[38:39]
	v_and_b32_e32 v1, 1, v1
	v_cmp_eq_u32_e64 s[70:71], 1, v1
	v_or_b32_e32 v1, 27, v236
	v_cmp_le_u32_e32 vcc, v1, v235
	v_mov_b32_e32 v140, v172
	v_mov_b32_e32 v141, v172
	v_cndmask_b32_e64 v2, 0, 1, vcc
	v_cmp_ge_u32_e32 vcc, v1, v235
	v_mov_b32_e32 v32, v172
	v_mov_b32_e32 v33, v172
	v_cndmask_b32_e64 v1, 0, 1, vcc
	v_cndmask_b32_e64 v1, v1, v2, s[38:39]
	v_and_b32_e32 v1, 1, v1
	v_cmp_eq_u32_e64 s[72:73], 1, v1
	v_mov_b32_e32 v1, v172
	v_mov_b32_e32 v2, v172
	v_mov_b32_e32 v34, v172
	v_mov_b32_e32 v35, v172
	v_mov_b32_e32 v36, v172
	v_mov_b32_e32 v37, v172
	v_mov_b32_e32 v38, v172
	v_mov_b32_e32 v39, v172
	v_mov_b32_e32 v40, v172
	v_mov_b32_e32 v41, v172
	v_mov_b32_e32 v42, v172
	v_mov_b32_e32 v43, v172
	v_mov_b32_e32 v44, v172
	v_mov_b32_e32 v45, v172
	v_mov_b32_e32 v46, v172
	v_mov_b32_e32 v47, v172
	v_mov_b32_e32 v142, v172
	v_mov_b32_e32 v143, v172
	v_mov_b32_e32 v48, v172
	v_mov_b32_e32 v49, v172
	v_mov_b32_e32 v50, v172
	v_mov_b32_e32 v51, v172
	v_mov_b32_e32 v52, v172
	v_mov_b32_e32 v53, v172
	v_mov_b32_e32 v54, v172
	v_mov_b32_e32 v55, v172
	v_mov_b32_e32 v56, v172
	v_mov_b32_e32 v57, v172
	v_mov_b32_e32 v58, v172
	v_mov_b32_e32 v59, v172
	v_mov_b32_e32 v60, v172
	v_mov_b32_e32 v61, v172
	v_mov_b32_e32 v62, v172
	v_mov_b32_e32 v63, v172
	s_waitcnt lgkmcnt(0)
	s_barrier
	v_lshl_add_u64 v[208:209], v[198:199], 1, v[208:209]
	v_lshl_add_u64 v[210:211], v[198:199], 1, v[210:211]
	v_lshl_add_u64 v[212:213], v[202:203], 1, v[212:213]
	v_lshl_add_u64 v[214:215], v[202:203], 1, v[214:215]
	s_mov_b32 s4, s36
	s_mov_b32 s5, s74
	v_lshl_add_u64 v[200:201], v[200:201], 1, s[4:5]
	v_lshl_add_u64 v[204:205], v[204:205], 1, s[4:5]
	v_and_b32_e32 v253, 0x3c0, v220
	v_lshlrev_b32_e32 v253, 4, v253
	v_sub_u32_e32 v234, v234, v253
	v_sub_u32_e32 v254, 0, v253
	v_ashrrev_i32_e32 v255, 31, v254
	v_lshl_add_u64 v[218:219], v[254:255], 0, v[218:219]
	s_mov_b32 s40, -1
	s_mov_b32 s41, 0
	s_movk_i32 s26, 0x800
	v_lshlrev_b32_e32 v254, 1, v236
	v_mov_b32_e32 v255, 0
	v_lshl_add_u64 v[216:217], v[254:255], 0, v[216:217]
	s_mov_b32 s4, 1
	s_cmp_lt_u32 s4, 8
	s_cselect_b32 s5, 7, 0x10f
	s_sub_i32 s5, s5, s4
	s_and_b64 vcc, s[38:39], exec
	s_cselect_b32 s20, s4, s5
	s_lshl_b32 s82, s20, 9
	s_mov_b32 s83, 0
	s_lshl_b32 s20, s20, 13
	s_mov_b32 s21, 0
	v_lshl_add_u64 v[82:83], v[218:219], 0, s[82:83]
	s_mov_b64 exec, s[40:41]
	global_load_dwordx4 v[112:115], v[82:83], off
	s_mov_b64 exec, -1
	v_lshl_add_u64 v[84:85], v[208:209], 0, s[20:21]
	global_load_dwordx4 v[96:99], v[84:85], off
	v_lshl_add_u64 v[86:87], v[210:211], 0, s[20:21]
	global_load_dwordx4 v[100:103], v[86:87], off
	v_lshl_add_u64 v[88:89], v[200:201], 0, s[20:21]
	global_load_dwordx4 v[104:107], v[88:89], off
	v_lshl_add_u64 v[90:91], v[212:213], 0, s[20:21]
	global_load_dwordx4 v[108:111], v[90:91], off
	v_lshl_add_u64 v[92:93], v[214:215], 0, s[20:21]
	global_load_dwordx4 v[116:119], v[92:93], off
	v_lshl_add_u64 v[94:95], v[204:205], 0, s[20:21]
	global_load_dwordx4 v[120:123], v[94:95], off
	s_waitcnt vmcnt(0)
; template <int DK>
; DI void scan_wg(const Params& p, char* smem, int grp, int dir, int hb) {
;     ...
;   auto gload = [&](int step) {
;     const size_t pos0 = (size_t)blk_of(step) * 32;
; #pragma unroll
;     for (int i = 0; i < QN; i++) {
;       const int id = tid + i * 256;
;       sq[i] = *(const bf16x8*)(Qb + (pos0 + id / CPR) * DK + (id % CPR) * 8);
;       sk[i] = *(const bf16x8*)(Kb + (pos0 + id / CPR) * DK + (id % CPR) * 8);
;       skt[i] = *(const bf16x8*)(KTb + (size_t)blk_of(step) * DK * 32 + id * 8);
;     }
;     if (tid < DK / 4) sd = *(const float4*)(Db + (size_t)blk_of(step) * DK + tid * 4);
;     vn0 = *(const bf16x8*)(VTb + (size_t)blk_of(step) * 128 * 32);
;     vn1 = *(const bf16x8*)(VTb + (size_t)blk_of(step) * 128 * 32 + 16);
;   };
;   auto lstore = [&](int buf) {
;     char* base = smem + buf * BUFB;
; #pragma unroll
;     for (int i = 0; i < QN; i++) {
;       const int id = tid + i * 256;
;       *(bf16x8*)(base + ((id / CPR) * QS + (id % CPR) * 8) * 2) = sq[i];
;       *(bf16x8*)(base + OFF_K + ((id / CPR) * QS + (id % CPR) * 8) * 2) = sk[i];
;       *(bf16x8*)(base + OFF_KT + ((id >> 2) * KTS + (id & 3) * 8) * 2) = skt[i];
;     }
;     if (tid < DK / 4) *(float4*)(base + OFF_D + tid * 16) = sd;
;   };
.Lhs_top:
	s_bitcmp1_b32 s30, 0
	s_cselect_b32 s0, 0x6e00, 0
	s_cselect_b32 s1, 0, 0x6e00
	s_add_i32 s4, s30, 1
	s_min_u32 s4, s4, 0x107
	s_cmp_lt_u32 s4, 8
	s_cselect_b32 s5, 7, 0x10f
	s_sub_i32 s5, s5, s4
	s_and_b64 vcc, s[38:39], exec
	s_cselect_b32 s4, s4, s5
	s_lshl_b32 s4, s4, 13
	s_mov_b32 s5, 0
	s_add_i32 s20, s30, 2
	s_min_u32 s20, s20, 0x107
	s_cmp_lt_u32 s20, 8
	s_cselect_b32 s21, 7, 0x10f
	s_sub_i32 s21, s21, s20
	s_and_b64 vcc, s[38:39], exec
	s_cselect_b32 s20, s20, s21
	s_lshl_b32 s82, s20, 9
	s_mov_b32 s83, 0
	s_lshl_b32 s20, s20, 13
	s_mov_b32 s21, 0
	v_lshl_add_u64 v[254:255], v[206:207], 0, s[4:5]
	v_lshl_add_u64 v[82:83], v[218:219], 0, s[82:83]
	v_lshl_add_u64 v[84:85], v[208:209], 0, s[20:21]
	v_lshl_add_u64 v[86:87], v[210:211], 0, s[20:21]
	v_lshl_add_u64 v[88:89], v[200:201], 0, s[20:21]
	v_lshl_add_u64 v[90:91], v[212:213], 0, s[20:21]
	v_lshl_add_u64 v[92:93], v[214:215], 0, s[20:21]
	v_lshl_add_u64 v[94:95], v[204:205], 0, s[20:21]
	v_add_u32_e32 v242, s1, v230
	v_add_u32_e32 v243, s1, v231
	v_add_u32_e32 v244, s1, v232
	v_add_u32_e32 v245, s1, v233
	v_add_u32_e32 v246, s1, v234
	global_load_dwordx4 v[132:135], v[254:255], off
	global_load_dwordx4 v[136:139], v[254:255], off offset:32
	s_mov_b64 exec, s[40:41]
	s_waitcnt vmcnt(10)
	ds_write_b128 v246, v[112:115] offset:27648
	global_load_dwordx4 v[112:115], v[82:83], off
	s_mov_b64 exec, -1
	s_waitcnt vmcnt(10)
	ds_write_b128 v242, v[96:99]
	global_load_dwordx4 v[96:99], v[84:85], off
	s_waitcnt vmcnt(10)
	ds_write_b128 v242, v[100:103] offset:8704
	global_load_dwordx4 v[100:103], v[86:87], off
	s_waitcnt vmcnt(10)
	ds_write_b128 v243, v[104:107] offset:17408
	global_load_dwordx4 v[104:107], v[88:89], off
	s_waitcnt vmcnt(10)
	ds_write_b128 v244, v[108:111]
	global_load_dwordx4 v[108:111], v[90:91], off
	s_waitcnt vmcnt(10)
	ds_write_b128 v244, v[116:119] offset:8704
	global_load_dwordx4 v[116:119], v[92:93], off
	s_waitcnt vmcnt(10)
	ds_write_b128 v245, v[120:123] offset:17408
	global_load_dwordx4 v[120:123], v[94:95], off
	v_add3_u32 v239, s0, v238, v196
	v_add3_u32 v240, s0, v237, v196
	v_lshl_or_b32 v241, v236, 2, s0
	ds_read_b128 v[172:175], v239 offset:8704
	ds_read_b128 v[176:179], v239
	ds_read_b128 v[180:183], v239 offset:8736
	ds_read_b128 v[184:187], v239 offset:32
	ds_read_b128 v[188:191], v239 offset:8768
	ds_read_b128 v[192:195], v239 offset:64
	s_waitcnt lgkmcnt(4)
	v_mfma_f32_32x32x16_bf16 v[64:79], v[172:175], v[176:179], 0
	ds_read_b128 v[172:175], v239 offset:8800
	ds_read_b128 v[176:179], v239 offset:96
	v_cvt_pk_bf16_f32 v140, v0, v1
	v_cvt_pk_bf16_f32 v141, v2, v3
	v_cvt_pk_bf16_f32 v142, v4, v5
	v_cvt_pk_bf16_f32 v143, v6, v7
	s_waitcnt lgkmcnt(4)
	v_mfma_f32_32x32x16_bf16 v[64:79], v[180:183], v[184:187], v[64:79]
	ds_read_b128 v[180:183], v239 offset:8832
	ds_read_b128 v[184:187], v239 offset:128
	v_cvt_pk_bf16_f32 v144, v8, v9
	v_cvt_pk_bf16_f32 v145, v10, v11
	v_cvt_pk_bf16_f32 v146, v12, v13
	v_cvt_pk_bf16_f32 v147, v14, v15
	s_waitcnt lgkmcnt(4)
	v_mfma_f32_32x32x16_bf16 v[64:79], v[188:191], v[192:195], v[64:79]
	ds_read_b128 v[188:191], v239 offset:8864
	ds_read_b128 v[192:195], v239 offset:160
	v_cvt_pk_bf16_f32 v148, v16, v17
	v_cvt_pk_bf16_f32 v149, v18, v19
	v_cvt_pk_bf16_f32 v150, v20, v21
	v_cvt_pk_bf16_f32 v151, v22, v23
	s_waitcnt lgkmcnt(4)
	v_mfma_f32_32x32x16_bf16 v[64:79], v[172:175], v[176:179], v[64:79]
	ds_read_b128 v[172:175], v239 offset:8896
	ds_read_b128 v[176:179], v239 offset:192
	v_cvt_pk_bf16_f32 v152, v24, v25
	v_cvt_pk_bf16_f32 v153, v26, v27
	v_cvt_pk_bf16_f32 v154, v28, v29
	v_cvt_pk_bf16_f32 v155, v30, v31
	s_waitcnt lgkmcnt(4)
	v_mfma_f32_32x32x16_bf16 v[64:79], v[180:183], v[184:187], v[64:79]
	ds_read_b128 v[180:183], v239 offset:8928
	ds_read_b128 v[184:187], v239 offset:224
	v_cvt_pk_bf16_f32 v156, v32, v33
	v_cvt_pk_bf16_f32 v157, v34, v35
	v_cvt_pk_bf16_f32 v158, v36, v37
	v_cvt_pk_bf16_f32 v159, v38, v39
	s_waitcnt lgkmcnt(4)
	v_mfma_f32_32x32x16_bf16 v[64:79], v[188:191], v[192:195], v[64:79]
	ds_read_b128 v[188:191], v240 offset:17408
	ds_read_b128 v[192:195], v240 offset:17440
	v_cvt_pk_bf16_f32 v160, v40, v41
	v_cvt_pk_bf16_f32 v161, v42, v43
	v_cvt_pk_bf16_f32 v162, v44, v45
	v_cvt_pk_bf16_f32 v163, v46, v47
	s_waitcnt lgkmcnt(4)
	v_mfma_f32_32x32x16_bf16 v[64:79], v[172:175], v[176:179], v[64:79]
	ds_read_b128 v[172:175], v240 offset:19968
	ds_read_b128 v[176:179], v240 offset:20000
	v_cvt_pk_bf16_f32 v164, v48, v49
	v_cvt_pk_bf16_f32 v165, v50, v51
	v_cvt_pk_bf16_f32 v166, v52, v53
	v_cvt_pk_bf16_f32 v167, v54, v55
	s_waitcnt lgkmcnt(4)
	v_mfma_f32_32x32x16_bf16 v[64:79], v[180:183], v[184:187], v[64:79]
	ds_read_b128 v[180:183], v240 offset:22528
	ds_read_b128 v[184:187], v240 offset:22560
	v_cvt_pk_bf16_f32 v168, v56, v57
	v_cvt_pk_bf16_f32 v169, v58, v59
	v_cvt_pk_bf16_f32 v170, v60, v61
	v_cvt_pk_bf16_f32 v171, v62, v63
	s_waitcnt lgkmcnt(5)
	v_mfma_f32_32x32x16_bf16 v[0:15], v[188:191], v[128:131], v[0:15]
	ds_read_b128 v[80:83], v241 offset:27648
	ds_read_b128 v[84:87], v241 offset:27680
	ds_read_b128 v[88:91], v241 offset:27712
	ds_read_b128 v[92:95], v241 offset:27744
	s_waitcnt lgkmcnt(8)
	v_mfma_f32_32x32x16_bf16 v[0:15], v[192:195], v[124:127], v[0:15]
	ds_read_b128 v[188:191], v240 offset:25088
	ds_read_b128 v[192:195], v240 offset:25120
	v_cndmask_b32_e64 v64, 0, v64, s[42:43]
	v_cndmask_b32_e64 v65, 0, v65, s[44:45]
	s_waitcnt lgkmcnt(9)
	v_mfma_f32_32x32x16_bf16 v[16:31], v[172:175], v[128:131], v[16:31]
	v_cndmask_b32_e64 v66, 0, v66, s[46:47]
	v_cndmask_b32_e64 v67, 0, v67, s[48:49]
	v_cndmask_b32_e64 v68, 0, v68, s[50:51]
	v_cndmask_b32_e64 v69, 0, v69, s[52:53]
	v_cndmask_b32_e64 v70, 0, v70, s[54:55]
	v_cndmask_b32_e64 v71, 0, v71, s[56:57]
	s_waitcnt lgkmcnt(8)
; DI u32 pack2(float a, float b) { f32x2v v = {a, b}; return __builtin_bit_cast(u32, __builtin_convertvector(v, bf16x2v)); }
; #define MFMA32(a, b, c) __builtin_amdgcn_mfma_f32_32x32x16_bf16((a), (b), (c), 0, 0, 0)
; template <int DK>
; DI void scan_wg(const Params& p, char* smem, int grp, int dir, int hb) {
;     ...
; #pragma unroll
;     for (int kt = 0; kt < NT; kt++) {
;       S[kt] = MFMA32(*(const bf16x8*)(KTs + kt * 32 * KTS), vf0, S[kt]);
;       S[kt] = MFMA32(*(const bf16x8*)(KTs + kt * 32 * KTS + 16), vf1, S[kt]);
; #pragma unroll
;       for (int g = 0; g < 4; g++) {
;         const float4 dv = *(const float4*)(Ds + kt * 32 + 8 * g);
;         S[kt][4 * g + 0] *= dv.x; S[kt][4 * g + 1] *= dv.y; S[kt][4 * g + 2] *= dv.z; S[kt][4 * g + 3] *= dv.w;
;       }
;     }
;     {
;       const int pos0 = blk * 32;
;       int rbase, rstride;
;       if (pos0 < CTX) { rbase = NLAT + b * CTX + pos0; rstride = 1; }
;       else if (grp == 0) { rbase = b * SEQ + pos0 - CTX; rstride = 1; }
;       else { const int pp = pos0 - CTX; rbase = b * SEQ + (pp & 127) * 64 + (pp >> 7); rstride = 64; }
;       u16* orow = Ob + (size_t)(rbase + r * rstride) * D + 4 * h;
; #pragma unroll
;       for (int g = 0; g < 4; g++)
;         *(uint2*)(orow + 8 * g) = make_uint2(pack2(oA[4 * g] + oB[4 * g], oA[4 * g + 1] + oB[4 * g + 1]),
;                                              pack2(oA[4 * g + 2] + oB[4 * g + 2], oA[4 * g + 3] + oB[4 * g + 3]));
;     }
;     if (step + 1 < NBLK) lstore((step + 1) & 1);
;     vf0 = vn0; vf1 = vn1;
;     __syncthreads();
	v_mfma_f32_32x32x16_bf16 v[16:31], v[176:179], v[124:127], v[16:31]
	ds_read_b128 v[172:175], v241 offset:27776
	ds_read_b128 v[176:179], v241 offset:27808
	v_cvt_pk_bf16_f32 v242, v64, v65
	v_cvt_pk_bf16_f32 v243, v66, v67
	v_cvt_pk_bf16_f32 v244, v68, v69
	v_cvt_pk_bf16_f32 v245, v70, v71
	v_cndmask_b32_e64 v72, 0, v72, s[58:59]
	s_waitcnt lgkmcnt(9)
	v_mfma_f32_32x32x16_bf16 v[32:47], v[180:183], v[128:131], v[32:47]
	v_cndmask_b32_e64 v73, 0, v73, s[60:61]
	v_cndmask_b32_e64 v74, 0, v74, s[62:63]
	v_cndmask_b32_e64 v75, 0, v75, s[64:65]
	v_cndmask_b32_e64 v76, 0, v76, s[66:67]
	v_cndmask_b32_e64 v77, 0, v77, s[68:69]
	v_cndmask_b32_e64 v78, 0, v78, s[70:71]
	s_waitcnt lgkmcnt(8)
	v_mfma_f32_32x32x16_bf16 v[32:47], v[184:187], v[124:127], v[32:47]
	ds_read_b128 v[180:183], v239
	ds_read_b128 v[184:187], v239 offset:32
	v_cndmask_b32_e64 v79, 0, v79, s[72:73]
	v_cvt_pk_bf16_f32 v246, v72, v73
	v_cvt_pk_bf16_f32 v247, v74, v75
	v_cvt_pk_bf16_f32 v248, v76, v77
	v_cvt_pk_bf16_f32 v249, v78, v79
	s_waitcnt lgkmcnt(5)
	v_mfma_f32_32x32x16_bf16 v[48:63], v[188:191], v[128:131], v[48:63]
	v_mul_f32_e32 v0, v0, v80
	v_mul_f32_e32 v1, v1, v81
	v_mul_f32_e32 v2, v2, v82
	v_mul_f32_e32 v3, v3, v83
	v_mul_f32_e32 v4, v4, v84
	v_mul_f32_e32 v5, v5, v85
	v_mul_f32_e32 v6, v6, v86
	v_mul_f32_e32 v7, v7, v87
	s_waitcnt lgkmcnt(4)
	v_mfma_f32_32x32x16_bf16 v[48:63], v[192:195], v[124:127], v[48:63]
	v_mul_f32_e32 v8, v8, v88
	v_mul_f32_e32 v9, v9, v89
	v_mul_f32_e32 v10, v10, v90
	v_mul_f32_e32 v11, v11, v91
	v_mul_f32_e32 v12, v12, v92
	v_mul_f32_e32 v13, v13, v93
	v_mul_f32_e32 v14, v14, v94
	v_mul_f32_e32 v15, v15, v95
	ds_read_b128 v[80:83], v241 offset:27840
	ds_read_b128 v[84:87], v241 offset:27872
	ds_read_b128 v[88:91], v239 offset:64
	ds_read_b128 v[92:95], v239 offset:96
	ds_read_b128 v[188:191], v241 offset:27904
	ds_read_b128 v[192:195], v241 offset:27936
	v_mfma_f32_32x32x16_bf16 v[64:79], v[128:131], v[242:245], 0
	s_waitcnt lgkmcnt(8)
	v_mul_f32_e32 v16, v16, v172
	v_mul_f32_e32 v17, v17, v173
	v_mul_f32_e32 v18, v18, v174
	v_mul_f32_e32 v19, v19, v175
	v_mul_f32_e32 v20, v20, v176
	v_mul_f32_e32 v21, v21, v177
	v_mul_f32_e32 v22, v22, v178
	v_mul_f32_e32 v23, v23, v179
	v_mfma_f32_32x32x16_bf16 v[64:79], v[124:127], v[246:249], v[64:79]
	ds_read_b128 v[172:175], v239 offset:128
	ds_read_b128 v[176:179], v239 offset:160
	ds_read_b128 v[242:245], v241 offset:27968
	ds_read_b128 v[246:249], v241 offset:28000
	s_waitcnt lgkmcnt(11)
	v_mfma_f32_32x32x16_bf16 v[64:79], v[140:143], v[180:183], v[64:79]
	ds_read_b128 v[180:183], v239 offset:192
	s_waitcnt lgkmcnt(9)
	v_mul_f32_e32 v24, v24, v80
	v_mul_f32_e32 v25, v25, v81
	v_mul_f32_e32 v26, v26, v82
	v_mul_f32_e32 v27, v27, v83
	v_mul_f32_e32 v28, v28, v84
	v_mul_f32_e32 v29, v29, v85
	v_mul_f32_e32 v30, v30, v86
	v_mul_f32_e32 v31, v31, v87
	ds_read_b128 v[80:83], v241 offset:28032
	ds_read_b128 v[84:87], v241 offset:28064
	v_mfma_f32_32x32x16_bf16 v[64:79], v[144:147], v[184:187], v[64:79]
	ds_read_b128 v[184:187], v239 offset:224
	s_waitcnt lgkmcnt(8)
	v_mul_f32_e32 v32, v32, v188
	v_mul_f32_e32 v33, v33, v189
	v_mul_f32_e32 v34, v34, v190
	v_mul_f32_e32 v35, v35, v191
	v_mul_f32_e32 v36, v36, v192
	v_mul_f32_e32 v37, v37, v193
	v_mul_f32_e32 v38, v38, v194
	v_mul_f32_e32 v39, v39, v195
	ds_read_b128 v[188:191], v241 offset:28096
	ds_read_b128 v[192:195], v241 offset:28128
	v_mfma_f32_32x32x16_bf16 v[64:79], v[148:151], v[88:91], v[64:79]
	s_waitcnt lgkmcnt(6)
	v_mul_f32_e32 v40, v40, v242
	v_mul_f32_e32 v41, v41, v243
	v_mul_f32_e32 v42, v42, v244
	v_mul_f32_e32 v43, v43, v245
	v_mul_f32_e32 v44, v44, v246
	v_mul_f32_e32 v45, v45, v247
	v_mul_f32_e32 v46, v46, v248
	v_mul_f32_e32 v47, v47, v249
	v_mfma_f32_32x32x16_bf16 v[64:79], v[152:155], v[92:95], v[64:79]
	s_waitcnt lgkmcnt(3)
	v_mul_f32_e32 v48, v48, v80
	v_mul_f32_e32 v49, v49, v81
	v_mul_f32_e32 v50, v50, v82
	v_mul_f32_e32 v51, v51, v83
	v_mul_f32_e32 v52, v52, v84
	v_mul_f32_e32 v53, v53, v85
	v_mul_f32_e32 v54, v54, v86
	v_mul_f32_e32 v55, v55, v87
	v_mfma_f32_32x32x16_bf16 v[64:79], v[156:159], v[172:175], v[64:79]
	s_waitcnt lgkmcnt(0)
	v_mul_f32_e32 v56, v56, v188
	v_mul_f32_e32 v57, v57, v189
	v_mul_f32_e32 v58, v58, v190
	v_mul_f32_e32 v59, v59, v191
	v_mul_f32_e32 v60, v60, v192
	v_mul_f32_e32 v61, v61, v193
	v_mul_f32_e32 v62, v62, v194
	v_mul_f32_e32 v63, v63, v195
	v_mfma_f32_32x32x16_bf16 v[64:79], v[160:163], v[176:179], v[64:79]
	s_mov_b32 s4, s30
	s_cmp_lt_u32 s4, 8
	s_cselect_b32 s5, 7, 0x10f
	s_sub_i32 s5, s5, s4
	s_and_b64 vcc, s[38:39], exec
	s_cselect_b32 s4, s4, s5
	s_lshl_b32 s5, s4, 5
	s_cmp_lt_i32 s4, 8
	s_cselect_b32 s4, s33, s24
	s_add_i32 s4, s4, s5
	v_or_b32_e32 v253, s4, v235
	v_mfma_f32_32x32x16_bf16 v[64:79], v[164:167], v[180:183], v[64:79]
	v_mad_u64_u32 v[254:255], s[20:21], v253, s26, v[216:217]
	v_mfma_f32_32x32x16_bf16 v[64:79], v[168:171], v[184:187], v[64:79]
	s_waitcnt vmcnt(7)
	v_mov_b64_e32 v[128:129], v[132:133]
	v_mov_b64_e32 v[130:131], v[134:135]
	v_mov_b64_e32 v[124:125], v[136:137]
	v_mov_b64_e32 v[126:127], v[138:139]
	s_add_i32 s75, s75, -1
	s_add_i32 s30, s30, 1
	s_nop 4
	v_cvt_pk_bf16_f32 v172, v64, v65
	v_cvt_pk_bf16_f32 v173, v66, v67
	v_cvt_pk_bf16_f32 v174, v68, v69
	v_cvt_pk_bf16_f32 v175, v70, v71
	v_cvt_pk_bf16_f32 v176, v72, v73
	v_cvt_pk_bf16_f32 v177, v74, v75
	v_cvt_pk_bf16_f32 v178, v76, v77
	v_cvt_pk_bf16_f32 v179, v78, v79
	s_nop 1
	v_permlane32_swap_b32_e32 v172, v174
	v_permlane32_swap_b32_e32 v173, v175
	v_permlane32_swap_b32_e32 v176, v178
	v_permlane32_swap_b32_e32 v177, v179
	global_store_dwordx4 v[254:255], v[172:175], off
	global_store_dwordx4 v[254:255], v[176:179], off offset:32
	s_cmpk_eq_i32 s30, 0x108
	s_waitcnt lgkmcnt(0)
	s_barrier
	s_cbranch_scc0 .Lhs_top
	s_waitcnt vmcnt(0)
	s_branch .LBB0_561
